# diff attention loop: first QK^T MFMA of each tile issued after the second pair of K-fragment reads (first LDS read latency overlapped with row-sum adds)
# speedup vs baseline: 1.0017x; 1.0017x over previous
; template <int D0> __device__ __forceinline__ void pv_one(f32x16& od, int vb, bf16x8 pa0, bf16x8 pa1, bf16x8 pa2, bf16x8 pa3) {
;     const s16x4 l0 = tr_read<v_rd_off(D0, 0, 0)>(vb), h0 = tr_read<v_rd_off(D0, 0, 1)>(vb), l1 = tr_read<v_rd_off(D0, 1, 0)>(vb), h1 = tr_read<v_rd_off(D0, 1, 1)>(vb);
;     const s16x4 l2 = tr_read<v_rd_off(D0, 2, 0)>(vb), h2 = tr_read<v_rd_off(D0, 2, 1)>(vb), l3 = tr_read<v_rd_off(D0, 3, 0)>(vb), h3 = tr_read<v_rd_off(D0, 3, 1)>(vb);
;     asm volatile("s_waitcnt lgkmcnt(0)" ::: "memory"); SBAR();
;     ...
;     od = __builtin_amdgcn_mfma_f32_32x32x16_bf16(pa0, PK(l0, h0), od, 0, 0, 0);
;     od = __builtin_amdgcn_mfma_f32_32x32x16_bf16(pa1, PK(l1, h1), od, 0, 0, 0);
;     od = __builtin_amdgcn_mfma_f32_32x32x16_bf16(pa2, PK(l2, h2), od, 0, 0, 0);
;     od = __builtin_amdgcn_mfma_f32_32x32x16_bf16(pa3, PK(l3, h3), od, 0, 0, 0);
;     ...
; }
; __device__ __forceinline__ void pv_d0(f32x16* o, int vb, bf16x8 pa0, bf16x8 pa1, bf16x8 pa2, bf16x8 pa3) {
;     pv_one<0>(o[0], vb, pa0, pa1, pa2, pa3); pv_one<1>(o[1], vb, pa0, pa1, pa2, pa3); pv_one<2>(o[2], vb, pa0, pa1, pa2, pa3); pv_one<3>(o[3], vb, pa0, pa1, pa2, pa3);
; }
; __device__ __forceinline__ void partialSM(f32x16& p0, f32x16& p1, float& m_reg, float& mn, float& alpha, const float C, const float thr) {
;     float pmax = p0[0];
; #pragma unroll
;     for (int r = 1; r < 16; ++r) pmax = fmaxf(pmax, p0[r]);
; #pragma unroll
;     for (int r = 0; r < 16; ++r) pmax = fmaxf(pmax, p1[r]);
;     { auto rr = __builtin_amdgcn_permlane32_swap(__float_as_uint(pmax), __float_as_uint(pmax), false, false);
;       pmax = fmaxf(__uint_as_float(rr[0]), __uint_as_float(rr[1])); }
;     if (__builtin_expect(__all(pmax - m_reg <= thr), 1)) { mn = m_reg; alpha = 1.f; }
;     else { mn = fmaxf(m_reg, pmax); alpha = __builtin_amdgcn_exp2f((m_reg - mn) * C); m_reg = mn; }
;     const float mnC = -mn * C;
; #pragma unroll
;     for (int r = 0; r < 16; ++r) p0[r] = fmaf(p0[r], C, mnC);
; #pragma unroll
;     for (int r = 0; r < 16; ++r) p1[r] = fmaf(p1[r], C, mnC);
; #pragma unroll
;     for (int r = 0; r < 16; ++r) p0[r] = __builtin_amdgcn_exp2f(p0[r]);
; }
; __device__ __forceinline__ void finishSM(f32x16& p0, f32x16& p1, float alpha, float& l_reg, bf16x8& pa0, bf16x8& pa1, bf16x8& pa2, bf16x8& pa3) {
; #pragma unroll
;     for (int r = 0; r < 16; ++r) p1[r] = __builtin_amdgcn_exp2f(p1[r]);
;     float ps = 0;
.LBB0_171:
	s_add_i32 s37, s52, -3
	ds_read_b128 v[64:67], v186 offset:40960
	ds_read_b128 v[68:71], v186 offset:45056
	v_exp_f32_e32 v143, v138
	v_add_f32_e32 v138, 0, v217
	v_add_f32_e32 v138, v219, v138
	v_add_f32_e32 v138, v208, v138
	v_add_f32_e32 v138, v218, v138
	v_add_f32_e32 v138, v153, v138
	ds_read_b128 v[204:207], v188 offset:40960
	ds_read_b128 v[220:223], v188 offset:45056
	v_add_f32_e32 v138, v216, v138
	v_add_f32_e32 v138, v152, v138
	v_add_f32_e32 v138, v202, v138
	s_waitcnt lgkmcnt(3)
	v_mfma_f32_32x32x16_bf16 v[80:95], v[64:67], v[110:113], 0
	s_waitcnt lgkmcnt(2)
	v_mfma_f32_32x32x16_bf16 v[64:79], v[68:71], v[110:113], 0
	v_add_f32_e32 v138, v149, v138
	v_add_f32_e32 v138, v151, v138
	v_add_f32_e32 v138, v147, v138
	v_add_f32_e32 v138, v150, v138
	v_add_f32_e32 v138, v145, v138
	v_exp_f32_e32 v191, v139
	v_add_f32_e32 v138, v148, v138
	s_waitcnt lgkmcnt(1)
	v_mfma_f32_32x32x16_bf16 v[80:95], v[204:207], v[106:109], v[80:95]
	v_exp_f32_e32 v136, v136
	v_add_f32_e32 v138, v144, v138
	v_exp_f32_e32 v137, v137
	v_add_f32_e32 v138, v146, v138
	v_exp_f32_e32 v130, v130
	v_add_f32_e32 v138, v143, v138
	v_exp_f32_e32 v131, v131
	s_waitcnt lgkmcnt(0)
	v_mfma_f32_32x32x16_bf16 v[64:79], v[220:223], v[106:109], v[64:79]
	ds_read_b128 v[204:207], v190 offset:40960
	ds_read_b128 v[220:223], v190 offset:45056
	v_add_f32_e32 v138, v191, v138
	v_exp_f32_e32 v128, v128
	v_add_f32_e32 v138, v136, v138
	v_exp_f32_e32 v129, v129
	v_add_f32_e32 v138, v137, v138
	v_exp_f32_e32 v126, v126
	s_waitcnt lgkmcnt(1)
	v_mfma_f32_32x32x16_bf16 v[80:95], v[204:207], v[102:105], v[80:95]
	v_add_f32_e32 v138, v130, v138
	v_exp_f32_e32 v127, v127
	v_add_f32_e32 v138, v131, v138
	v_exp_f32_e32 v200, v140
	v_add_f32_e32 v138, v128, v138
	v_exp_f32_e32 v210, v141
	v_add_f32_e32 v138, v129, v138
	s_waitcnt lgkmcnt(0)
	v_mfma_f32_32x32x16_bf16 v[64:79], v[220:223], v[102:105], v[64:79]
	ds_read_b128 v[204:207], v192 offset:40960
	ds_read_b128 v[220:223], v192 offset:45056
	v_exp_f32_e32 v134, v134
	v_add_f32_e32 v138, v126, v138
	v_exp_f32_e32 v135, v135
	v_add_f32_e32 v138, v127, v138
	v_exp_f32_e32 v132, v132
	v_add_f32_e32 v138, v200, v138
	s_waitcnt lgkmcnt(1)
	v_mfma_f32_32x32x16_bf16 v[80:95], v[204:207], v[98:101], v[80:95]
	v_exp_f32_e32 v133, v133
	v_add_f32_e32 v138, v210, v138
	v_add_f32_e32 v138, v134, v138
	v_add_f32_e32 v138, v135, v138
	v_add_f32_e32 v138, v132, v138
	v_add_f32_e32 v196, v133, v138
	v_mov_b32_e32 v198, v196
	s_waitcnt lgkmcnt(0)
	v_mfma_f32_32x32x16_bf16 v[64:79], v[220:223], v[98:101], v[64:79]
	ds_read_b64_tr_b16 v[220:221], v180 offset:0x1000
	ds_read_b64_tr_b16 v[222:223], v180 offset:0x1800
	ds_read_b64_tr_b16 v[224:225], v180 offset:0x2000
	ds_read_b64_tr_b16 v[226:227], v180 offset:0x2800
	ds_read_b64_tr_b16 v[228:229], v180 offset:0x3000
	ds_read_b64_tr_b16 v[230:231], v180 offset:0x3800
	v_cvt_pk_bf16_f32 v138, v217, v219
	v_cvt_pk_bf16_f32 v139, v208, v218
	v_cvt_pk_bf16_f32 v140, v153, v216
	ds_read_b64_tr_b16 v[216:217], v180 offset:0
	ds_read_b64_tr_b16 v[218:219], v180 offset:0x800
	v_permlane32_swap_b32_e32 v196, v198
	v_cvt_pk_bf16_f32 v141, v152, v202
	v_permlane32_swap_b32_e32 v138, v140
	v_cvt_pk_bf16_f32 v204, v149, v151
	v_cvt_pk_bf16_f32 v205, v147, v150
	v_cvt_pk_bf16_f32 v206, v145, v148
	v_cvt_pk_bf16_f32 v207, v144, v146
	v_cvt_pk_bf16_f32 v144, v143, v191
	v_cvt_pk_bf16_f32 v145, v136, v137
	v_cvt_pk_bf16_f32 v146, v130, v131
	v_cvt_pk_bf16_f32 v147, v128, v129
	v_cvt_pk_bf16_f32 v148, v126, v127
	v_cvt_pk_bf16_f32 v149, v200, v210
	v_cvt_pk_bf16_f32 v150, v134, v135
	v_cvt_pk_bf16_f32 v151, v132, v133
	v_permlane32_swap_b32_e32 v139, v141
	v_permlane32_swap_b32_e32 v204, v206
	v_permlane32_swap_b32_e32 v205, v207
	v_permlane32_swap_b32_e32 v144, v146
	v_permlane32_swap_b32_e32 v145, v147
	v_permlane32_swap_b32_e32 v148, v150
	v_permlane32_swap_b32_e32 v149, v151
	s_cmp_lt_u32 s37, 30
	s_cselect_b32 s14, 0, 0xffffffe0
	s_cselect_b32 s15, s18, s86
	s_add_i32 s14, s14, s52
	s_lshl_b32 s14, s14, 6
	s_add_i32 s14, s14, s15
	s_sub_i32 s14, s14, 64
	s_ashr_i32 s15, s14, 31
	v_lshl_add_u64 v[126:127], s[14:15], 0, v[164:165]
	v_lshl_add_u64 v[130:131], v[168:169], 0, s[14:15]
	v_mad_u64_u32 v[128:129], s[38:39], v126, s9, v[170:171]
	v_mad_u64_u32 v[132:133], s[38:39], v130, s9, v[170:171]
	v_mad_i32_i24 v129, v127, s9, v129
	v_mad_i32_i24 v133, v131, s9, v133
	v_mad_i64_i32 v[134:135], s[14:15], s14, v195, v[166:167]
	global_load_dwordx4 v[126:129], v[128:129], off
	s_nop 0
	global_load_dwordx4 v[130:133], v[132:133], off
	s_nop 0
	global_load_dwordx4 v[134:137], v[134:135], off
	s_waitcnt lgkmcnt(0)
	s_nop 0
	v_mfma_f32_32x32x16_bf16 v[48:63], v[138:141], v[216:219], v[48:63]
	ds_read_b64_tr_b16 v[216:217], v180 offset:0x200
	ds_read_b64_tr_b16 v[218:219], v180 offset:0xa00
	v_max_f32_e32 v238, v81, v81
	v_max_f32_e32 v239, v80, v80
	v_max_f32_e32 v238, v239, v238
	v_max3_f32 v238, v238, v82, v83
	v_max3_f32 v238, v238, v84, v85
	v_max3_f32 v238, v238, v86, v87
	v_mfma_f32_32x32x16_bf16 v[48:63], v[204:207], v[220:223], v[48:63]
	ds_read_b64_tr_b16 v[220:221], v180 offset:0x1200
	ds_read_b64_tr_b16 v[222:223], v180 offset:0x1a00
	v_max3_f32 v238, v238, v88, v89
	v_max3_f32 v238, v238, v90, v91
	v_max3_f32 v238, v238, v92, v93
	v_max3_f32 v238, v238, v94, v95
	v_max3_f32 v238, v238, v64, v65
	v_max3_f32 v238, v238, v66, v67
	v_mfma_f32_32x32x16_bf16 v[48:63], v[144:147], v[224:227], v[48:63]
	ds_read_b64_tr_b16 v[224:225], v180 offset:0x2200
	ds_read_b64_tr_b16 v[226:227], v180 offset:0x2a00
	v_max3_f32 v238, v238, v68, v69
	v_max3_f32 v238, v238, v70, v71
	v_max3_f32 v238, v238, v72, v73
	v_max3_f32 v238, v238, v74, v75
	v_max3_f32 v238, v238, v76, v77
	v_max3_f32 v238, v238, v78, v79
	v_mfma_f32_32x32x16_bf16 v[48:63], v[148:151], v[228:231], v[48:63]
	ds_read_b64_tr_b16 v[228:229], v180 offset:0x3200
	ds_read_b64_tr_b16 v[230:231], v180 offset:0x3a00
	v_mov_b32_e32 v239, v238
	s_nop 1
	v_permlane32_swap_b32_e32 v238, v239
	v_max_f32_e32 v239, v239, v239
	v_max_f32_e32 v238, v238, v238
	v_max_f32_e32 v238, v238, v239
	s_waitcnt lgkmcnt(0)
; #define SBAR() __builtin_amdgcn_sched_barrier(0)
; template <int OFF> __device__ __forceinline__ s16x4 tr_read(int vb) { s16x4 r; asm volatile("ds_read_b64_tr_b16 %0, %1 offset:%2" : "=&v"(r) : "v"(vb), "i"(OFF) : "memory"); return r; }
; template <int D0> __device__ __forceinline__ void pv_one(f32x16& od, int vb, bf16x8 pa0, bf16x8 pa1, bf16x8 pa2, bf16x8 pa3) {
;     const s16x4 l0 = tr_read<v_rd_off(D0, 0, 0)>(vb), h0 = tr_read<v_rd_off(D0, 0, 1)>(vb), l1 = tr_read<v_rd_off(D0, 1, 0)>(vb), h1 = tr_read<v_rd_off(D0, 1, 1)>(vb);
;     const s16x4 l2 = tr_read<v_rd_off(D0, 2, 0)>(vb), h2 = tr_read<v_rd_off(D0, 2, 1)>(vb), l3 = tr_read<v_rd_off(D0, 3, 0)>(vb), h3 = tr_read<v_rd_off(D0, 3, 1)>(vb);
;     asm volatile("s_waitcnt lgkmcnt(0)" ::: "memory"); SBAR();
;     ...
;     od = __builtin_amdgcn_mfma_f32_32x32x16_bf16(pa0, PK(l0, h0), od, 0, 0, 0);
;     od = __builtin_amdgcn_mfma_f32_32x32x16_bf16(pa1, PK(l1, h1), od, 0, 0, 0);
;     od = __builtin_amdgcn_mfma_f32_32x32x16_bf16(pa2, PK(l2, h2), od, 0, 0, 0);
;     od = __builtin_amdgcn_mfma_f32_32x32x16_bf16(pa3, PK(l3, h3), od, 0, 0, 0);
;     ...
; }
; __device__ __forceinline__ void pv_d0(f32x16* o, int vb, bf16x8 pa0, bf16x8 pa1, bf16x8 pa2, bf16x8 pa3) {
;     pv_one<0>(o[0], vb, pa0, pa1, pa2, pa3); pv_one<1>(o[1], vb, pa0, pa1, pa2, pa3); pv_one<2>(o[2], vb, pa0, pa1, pa2, pa3); pv_one<3>(o[3], vb, pa0, pa1, pa2, pa3);
; }
; __device__ __forceinline__ void partialSM(f32x16& p0, f32x16& p1, float& m_reg, float& mn, float& alpha, const float C, const float thr) {
;     float pmax = p0[0];
; #pragma unroll
;     for (int r = 1; r < 16; ++r) pmax = fmaxf(pmax, p0[r]);
; #pragma unroll
;     for (int r = 0; r < 16; ++r) pmax = fmaxf(pmax, p1[r]);
;     { auto rr = __builtin_amdgcn_permlane32_swap(__float_as_uint(pmax), __float_as_uint(pmax), false, false);
;       pmax = fmaxf(__uint_as_float(rr[0]), __uint_as_float(rr[1])); }
;     if (__builtin_expect(__all(pmax - m_reg <= thr), 1)) { mn = m_reg; alpha = 1.f; }
;     else { mn = fmaxf(m_reg, pmax); alpha = __builtin_amdgcn_exp2f((m_reg - mn) * C); m_reg = mn; }
;     const float mnC = -mn * C;
; #pragma unroll
;     for (int r = 0; r < 16; ++r) p0[r] = fmaf(p0[r], C, mnC);
; #pragma unroll
;     for (int r = 0; r < 16; ++r) p1[r] = fmaf(p1[r], C, mnC);
; #pragma unroll
;     for (int r = 0; r < 16; ++r) p0[r] = __builtin_amdgcn_exp2f(p0[r]);
; }
	v_mfma_f32_32x32x16_bf16 v[32:47], v[138:141], v[216:219], v[32:47]
	ds_read_b64_tr_b16 v[216:217], v180 offset:0x400
	ds_read_b64_tr_b16 v[218:219], v180 offset:0xc00
	v_sub_f32_e32 v239, v238, v142
	v_cmp_ge_f32_e32 vcc, s76, v239
	v_max_f32_e32 v239, v142, v142
	v_max_f32_e32 v238, v239, v238
	v_sub_f32_e32 v239, v142, v238
	v_mul_f32_e32 v239, 0x3e38aa3b, v239
	v_mfma_f32_32x32x16_bf16 v[32:47], v[204:207], v[220:223], v[32:47]
	ds_read_b64_tr_b16 v[220:221], v180 offset:0x1400
	ds_read_b64_tr_b16 v[222:223], v180 offset:0x1c00
	v_exp_f32_e32 v239, v239
	s_cmp_eq_u64 vcc, exec
	s_cselect_b64 s[14:15], -1, 0
	v_cndmask_b32_e64 v200, v239, 1.0, s[14:15]
	v_cmp_gt_f32_e32 vcc, 1.0, v200
	v_mfma_f32_32x32x16_bf16 v[32:47], v[144:147], v[224:227], v[32:47]
	ds_read_b64_tr_b16 v[224:225], v180 offset:0x2400
	ds_read_b64_tr_b16 v[226:227], v180 offset:0x2c00
	v_cndmask_b32_e64 v241, v238, v142, s[14:15]
	v_mul_f32_e32 v239, 0xbe38aa3b, v241
	v_fmamk_f32 v80, v80, 0x3e38aa3b, v239
	v_fmamk_f32 v81, v81, 0x3e38aa3b, v239
	v_mfma_f32_32x32x16_bf16 v[32:47], v[148:151], v[228:231], v[32:47]
	ds_read_b64_tr_b16 v[228:229], v180 offset:0x3400
	ds_read_b64_tr_b16 v[230:231], v180 offset:0x3c00
	v_fmamk_f32 v82, v82, 0x3e38aa3b, v239
	v_fmamk_f32 v83, v83, 0x3e38aa3b, v239
	v_fmamk_f32 v84, v84, 0x3e38aa3b, v239
	v_fmamk_f32 v85, v85, 0x3e38aa3b, v239
	s_waitcnt lgkmcnt(0)
	v_mfma_f32_32x32x16_bf16 v[16:31], v[138:141], v[216:219], v[16:31]
	ds_read_b64_tr_b16 v[216:217], v180 offset:0x600
	ds_read_b64_tr_b16 v[218:219], v180 offset:0xe00
	v_fmamk_f32 v86, v86, 0x3e38aa3b, v239
	v_fmamk_f32 v87, v87, 0x3e38aa3b, v239
	v_fmamk_f32 v88, v88, 0x3e38aa3b, v239
	v_fmamk_f32 v89, v89, 0x3e38aa3b, v239
	v_mfma_f32_32x32x16_bf16 v[16:31], v[204:207], v[220:223], v[16:31]
	ds_read_b64_tr_b16 v[220:221], v180 offset:0x1600
	ds_read_b64_tr_b16 v[222:223], v180 offset:0x1e00
	v_fmamk_f32 v90, v90, 0x3e38aa3b, v239
	v_fmamk_f32 v91, v91, 0x3e38aa3b, v239
	v_fmamk_f32 v92, v92, 0x3e38aa3b, v239
	v_fmamk_f32 v93, v93, 0x3e38aa3b, v239
	v_mfma_f32_32x32x16_bf16 v[16:31], v[144:147], v[224:227], v[16:31]
	ds_read_b64_tr_b16 v[224:225], v180 offset:0x2600
	ds_read_b64_tr_b16 v[226:227], v180 offset:0x2e00
	v_fmamk_f32 v94, v94, 0x3e38aa3b, v239
	v_fmamk_f32 v95, v95, 0x3e38aa3b, v239
	v_mfma_f32_32x32x16_bf16 v[16:31], v[148:151], v[228:231], v[16:31]
	ds_read_b64_tr_b16 v[228:229], v180 offset:0x3600
	ds_read_b64_tr_b16 v[230:231], v180 offset:0x3e00
	v_exp_f32_e32 v153, v81
	v_exp_f32_e32 v152, v83
	v_exp_f32_e32 v142, v88
	v_exp_f32_e32 v143, v90
	s_waitcnt lgkmcnt(0)
	v_mfma_f32_32x32x16_bf16 v[0:15], v[138:141], v[216:219], v[0:15]
	v_mfma_f32_32x32x16_bf16 v[0:15], v[204:207], v[220:223], v[0:15]
	v_exp_f32_e32 v138, v80
	v_mfma_f32_32x32x16_bf16 v[0:15], v[144:147], v[224:227], v[0:15]
	v_exp_f32_e32 v144, v92
	v_exp_f32_e32 v147, v93
	v_exp_f32_e32 v145, v94
	v_exp_f32_e32 v146, v95
	v_exp_f32_e32 v139, v82
	v_mfma_f32_32x32x16_bf16 v[0:15], v[148:151], v[228:231], v[0:15]
	v_exp_f32_e32 v140, v84
	v_exp_f32_e32 v141, v86
	s_barrier
	s_waitcnt vmcnt(5)
	ds_write_b128 v181, v[114:117]
	s_waitcnt vmcnt(4)
	ds_write_b128 v184, v[118:121]
	s_waitcnt vmcnt(3)
	ds_write_b128 v182, v[122:125] offset:32768
	s_cbranch_vccz .LBB0_175
	s_and_saveexec_b64 s[38:39], s[12:13]
	ds_write_b32 v177, v200 offset:49280
	s_or_b64 exec, exec, s[38:39]
	s_waitcnt lgkmcnt(0)
	v_add_u32_e32 v242, v161, v96
	ds_read_b128 v[244:247], v242 offset:49376
	ds_read_b128 v[148:151], v242 offset:49344
	ds_read_b128 v[204:207], v242 offset:49312
	ds_read_b128 v[216:219], v242 offset:49280
	s_waitcnt lgkmcnt(3)
	v_pk_mul_f32 v[60:61], v[60:61], v[244:245]
	s_waitcnt lgkmcnt(2)
	v_pk_mul_f32 v[56:57], v[56:57], v[148:149]
	s_waitcnt lgkmcnt(1)
	v_pk_mul_f32 v[52:53], v[52:53], v[204:205]
	v_pk_mul_f32 v[62:63], v[62:63], v[246:247]
	v_pk_mul_f32 v[58:59], v[58:59], v[150:151]
	v_pk_mul_f32 v[54:55], v[54:55], v[206:207]
	s_waitcnt lgkmcnt(0)
	v_pk_mul_f32 v[50:51], v[50:51], v[218:219]
	v_pk_mul_f32 v[48:49], v[48:49], v[216:217]
	v_pk_mul_f32 v[44:45], v[44:45], v[244:245]
	v_pk_mul_f32 v[40:41], v[40:41], v[148:149]
	v_pk_mul_f32 v[36:37], v[36:37], v[204:205]
	v_pk_mul_f32 v[46:47], v[46:47], v[246:247]
	v_pk_mul_f32 v[42:43], v[42:43], v[150:151]
	v_pk_mul_f32 v[38:39], v[38:39], v[206:207]
	v_pk_mul_f32 v[34:35], v[34:35], v[218:219]
	v_pk_mul_f32 v[32:33], v[32:33], v[216:217]
	v_pk_mul_f32 v[28:29], v[28:29], v[244:245]
	v_pk_mul_f32 v[24:25], v[24:25], v[148:149]
	v_pk_mul_f32 v[20:21], v[20:21], v[204:205]
	v_pk_mul_f32 v[30:31], v[30:31], v[246:247]
	v_pk_mul_f32 v[26:27], v[26:27], v[150:151]
	v_pk_mul_f32 v[22:23], v[22:23], v[206:207]
	v_pk_mul_f32 v[18:19], v[18:19], v[218:219]
	v_pk_mul_f32 v[16:17], v[16:17], v[216:217]
	v_pk_mul_f32 v[12:13], v[12:13], v[244:245]
	v_pk_mul_f32 v[8:9], v[8:9], v[148:149]
	v_pk_mul_f32 v[4:5], v[4:5], v[204:205]
	v_pk_mul_f32 v[14:15], v[14:15], v[246:247]
	v_pk_mul_f32 v[10:11], v[10:11], v[150:151]
	v_pk_mul_f32 v[6:7], v[6:7], v[206:207]
	v_pk_mul_f32 v[2:3], v[2:3], v[218:219]
	v_pk_mul_f32 v[0:1], v[0:1], v[216:217]
; #define SBAR() __builtin_amdgcn_sched_barrier(0)
; #define SLOAD(i, j) do { const long rb_ = KROW(j); sr_[i].vs0 = *(const bf16x8*)(a.V + (rb_ + sr) * LDV + sc); sr_[i].vs1 = *(const bf16x8*)(a.V + (rb_ + 32 + sr) * LDV + sc); \
;     _Pragma("unroll") for (int c_ = 0; c_ < KCH; ++c_) sr_[i].ks[c_] = *(const bf16x8*)(kptr[c_] + rb_ * kld[c_]); } while (0)
; __device__ __forceinline__ void finishSM(f32x16& p0, f32x16& p1, float alpha, float& l_reg, bf16x8& pa0, bf16x8& pa1, bf16x8& pa2, bf16x8& pa3) {
; #pragma unroll
;     for (int r = 0; r < 16; ++r) p1[r] = __builtin_amdgcn_exp2f(p1[r]);
;     float ps = 0;
; #pragma unroll
;     for (int r = 0; r < 16; ++r) ps += p0[r];
; #pragma unroll
;     for (int r = 0; r < 16; ++r) ps += p1[r];
;     { auto rr = __builtin_amdgcn_permlane32_swap(__float_as_uint(ps), __float_as_uint(ps), false, false);
;       ps = __uint_as_float(rr[0]) + __uint_as_float(rr[1]); }
;     l_reg = l_reg * alpha + ps;
;     ...
;     PK4(p0, 0, pa0); PK4(p0, 8, pa1); PK4(p1, 0, pa2); PK4(p1, 8, pa3);
;     ...
; }
; template <int DQK, int DK1, int LDQ, int LDK, int LDKR, int LDV, int NQL, int SDEPTH>
; __device__ __forceinline__ void attn_core(const AttnArgs& a, char* lds, f32x16 (&o)[4]) {
;     ...
;         SBAR(); QKT(pA0, pA1, K_lds);
;         finishSM(pB0, pB1, alB, l_reg, pa0, pa1, pa2, pa3); SBAR();
;         if (SDEPTH == 1 || j + 3 < NT) SLOAD(SE, j + 1 + SDEPTH); SBAR();
.LBB0_175:
	v_mov_b32_e32 v202, v241
	v_mul_f32_e32 v204, 0xbe38aa3b, v202
	v_exp_f32_e32 v151, v85
	v_exp_f32_e32 v150, v87
	v_exp_f32_e32 v149, v89
	v_exp_f32_e32 v148, v91
	v_fmamk_f32 v222, v64, 0x3e38aa3b, v204
	v_fmamk_f32 v223, v65, 0x3e38aa3b, v204
	v_fmamk_f32 v224, v66, 0x3e38aa3b, v204
	v_fmamk_f32 v225, v67, 0x3e38aa3b, v204
	v_fmamk_f32 v226, v68, 0x3e38aa3b, v204
	v_fmamk_f32 v208, v69, 0x3e38aa3b, v204
	v_fmamk_f32 v216, v70, 0x3e38aa3b, v204
	v_fmamk_f32 v217, v71, 0x3e38aa3b, v204
	v_fmamk_f32 v218, v72, 0x3e38aa3b, v204
	v_fmamk_f32 v219, v73, 0x3e38aa3b, v204
	v_fmamk_f32 v220, v74, 0x3e38aa3b, v204
	v_fmamk_f32 v221, v75, 0x3e38aa3b, v204
	v_fmamk_f32 v206, v76, 0x3e38aa3b, v204
	v_fmamk_f32 v227, v77, 0x3e38aa3b, v204
	v_fmamk_f32 v228, v78, 0x3e38aa3b, v204
	v_fmac_f32_e32 v204, 0x3e38aa3b, v79
	s_waitcnt lgkmcnt(0)
	s_barrier
	ds_read_b128 v[64:67], v186 offset:32768
	ds_read_b128 v[68:71], v186 offset:36864
	v_exp_f32_e32 v205, v223
	v_exp_f32_e32 v223, v204
	v_add_f32_e32 v204, 0, v138
	v_add_f32_e32 v204, v153, v204
	v_add_f32_e32 v204, v139, v204
	v_add_f32_e32 v204, v152, v204
	v_add_f32_e32 v204, v140, v204
	ds_read_b128 v[230:233], v188 offset:32768
	ds_read_b128 v[234:237], v188 offset:36864
	v_add_f32_e32 v204, v151, v204
	v_add_f32_e32 v204, v141, v204
	v_add_f32_e32 v204, v150, v204
	s_waitcnt lgkmcnt(3)
	v_mfma_f32_32x32x16_bf16 v[80:95], v[64:67], v[110:113], 0
	s_waitcnt lgkmcnt(2)
	v_mfma_f32_32x32x16_bf16 v[64:79], v[68:71], v[110:113], 0
	v_add_f32_e32 v204, v142, v204
	v_add_f32_e32 v204, v149, v204
	v_add_f32_e32 v204, v143, v204
	v_add_f32_e32 v204, v148, v204
	v_exp_f32_e32 v191, v222
	v_add_f32_e32 v204, v144, v204
	v_add_f32_e32 v204, v147, v204
	s_waitcnt lgkmcnt(1)
	v_mfma_f32_32x32x16_bf16 v[80:95], v[230:233], v[106:109], v[80:95]
	v_exp_f32_e32 v207, v224
	v_add_f32_e32 v204, v145, v204
	v_exp_f32_e32 v210, v225
	v_add_f32_e32 v204, v146, v204
	v_exp_f32_e32 v211, v226
	v_add_f32_e32 v204, v191, v204
	v_exp_f32_e32 v208, v208
	s_waitcnt lgkmcnt(0)
	v_mfma_f32_32x32x16_bf16 v[64:79], v[234:237], v[106:109], v[64:79]
	ds_read_b128 v[230:233], v190 offset:32768
	ds_read_b128 v[234:237], v190 offset:36864
	v_add_f32_e32 v204, v205, v204
	v_exp_f32_e32 v212, v216
	v_add_f32_e32 v204, v207, v204
	v_exp_f32_e32 v213, v217
	v_add_f32_e32 v204, v210, v204
	v_exp_f32_e32 v216, v218
	s_waitcnt lgkmcnt(1)
	v_mfma_f32_32x32x16_bf16 v[80:95], v[230:233], v[102:105], v[80:95]
	v_add_f32_e32 v204, v211, v204
	v_exp_f32_e32 v217, v219
	v_add_f32_e32 v204, v208, v204
	v_exp_f32_e32 v218, v220
	v_add_f32_e32 v204, v212, v204
	v_exp_f32_e32 v219, v221
	v_add_f32_e32 v204, v213, v204
	s_waitcnt lgkmcnt(0)
	v_mfma_f32_32x32x16_bf16 v[64:79], v[234:237], v[102:105], v[64:79]
	ds_read_b128 v[230:233], v192 offset:32768
	ds_read_b128 v[234:237], v192 offset:36864
	v_exp_f32_e32 v220, v206
	v_add_f32_e32 v204, v216, v204
	v_exp_f32_e32 v221, v227
	v_add_f32_e32 v204, v217, v204
	v_exp_f32_e32 v222, v228
	v_add_f32_e32 v204, v218, v204
	s_waitcnt lgkmcnt(1)
	v_mfma_f32_32x32x16_bf16 v[80:95], v[230:233], v[98:101], v[80:95]
	v_add_f32_e32 v204, v219, v204
	v_add_f32_e32 v204, v220, v204
	v_add_f32_e32 v204, v221, v204
	v_add_f32_e32 v204, v222, v204
	v_add_f32_e32 v204, v223, v204
	v_mov_b32_e32 v206, v204
	v_cvt_pk_bf16_f32 v138, v138, v153
	s_waitcnt lgkmcnt(0)
	v_mfma_f32_32x32x16_bf16 v[64:79], v[234:237], v[98:101], v[64:79]
	ds_read_b64_tr_b16 v[224:225], v179 offset:0x2000
	ds_read_b64_tr_b16 v[226:227], v179 offset:0x2800
	ds_read_b64_tr_b16 v[228:229], v179 offset:0x3000
	ds_read_b64_tr_b16 v[230:231], v179 offset:0x3800
	v_cvt_pk_bf16_f32 v139, v139, v152
	v_cvt_pk_bf16_f32 v140, v140, v151
	v_cvt_pk_bf16_f32 v141, v141, v150
	v_cvt_pk_bf16_f32 v142, v142, v149
	v_cvt_pk_bf16_f32 v143, v143, v148
	v_cvt_pk_bf16_f32 v144, v144, v147
	v_cvt_pk_bf16_f32 v145, v145, v146
	v_cvt_pk_bf16_f32 v146, v191, v205
	v_cvt_pk_bf16_f32 v147, v207, v210
	v_cvt_pk_bf16_f32 v148, v211, v208
	v_cvt_pk_bf16_f32 v149, v212, v213
	v_cvt_pk_bf16_f32 v150, v216, v217
	v_cvt_pk_bf16_f32 v151, v218, v219
	v_cvt_pk_bf16_f32 v152, v220, v221
	v_cvt_pk_bf16_f32 v153, v222, v223
	ds_read_b64_tr_b16 v[216:217], v179 offset:0
	ds_read_b64_tr_b16 v[218:219], v179 offset:0x800
	ds_read_b64_tr_b16 v[220:221], v179 offset:0x1000
	ds_read_b64_tr_b16 v[222:223], v179 offset:0x1800
	v_permlane32_swap_b32_e32 v204, v206
	v_permlane32_swap_b32_e32 v138, v140
	v_permlane32_swap_b32_e32 v139, v141
	v_permlane32_swap_b32_e32 v142, v144
	v_permlane32_swap_b32_e32 v143, v145
	v_permlane32_swap_b32_e32 v146, v148
	v_permlane32_swap_b32_e32 v147, v149
	v_permlane32_swap_b32_e32 v150, v152
	v_permlane32_swap_b32_e32 v151, v153
	s_cmp_gt_u32 s37, 32
	s_cbranch_scc1 .LBB0_177
	s_cmp_lt_u32 s37, 29
	s_cselect_b32 s14, 0, 0xffffffe0
	s_cselect_b32 s15, s18, s86
	s_add_i32 s14, s14, s52
	s_lshl_b32 s14, s14, 6
	s_add_i32 s14, s14, s15
	s_ashr_i32 s15, s14, 31
	v_lshl_add_u64 v[114:115], s[14:15], 0, v[164:165]
	v_lshl_add_u64 v[118:119], v[168:169], 0, s[14:15]
	v_mad_u64_u32 v[116:117], s[38:39], v114, s9, v[170:171]
	v_mad_u64_u32 v[120:121], s[38:39], v118, s9, v[170:171]
	v_mad_i32_i24 v117, v115, s9, v117
	v_mad_i32_i24 v121, v119, s9, v121
	v_mad_i64_i32 v[122:123], s[14:15], s14, v195, v[166:167]
	global_load_dwordx4 v[114:117], v[116:117], off
	s_nop 0
	global_load_dwordx4 v[118:121], v[120:121], off
	s_nop 0
	global_load_dwordx4 v[122:125], v[122:123], off
